# attention re-tiled to 32x32x16 bf16 MFMA (same operand/accumulate types), hand-written loop, last tile and epilogue; no-op steps skip their grid barrier
# speedup vs baseline: 1.2022x; 1.0038x over previous
.LBB0_20:
	s_add_u32 s54, s54, 1
	s_addc_u32 s55, s55, 0
	s_cmp_eq_u32 s54, 6
	s_cbranch_scc0 .Lnop_a
	s_mov_b32 s54, 10
.Lnop_a:
	s_cmp_eq_u32 s54, 26
	s_cbranch_scc0 .Lnop_b
	s_mov_b32 s54, 30
.Lnop_b:
	s_cmp_eq_u32 s54, 40
	s_cbranch_scc0 .LBB0_21
	s_getpc_b64 s[98:99]

.LBB0_934:
	s_add_u32 s12, s8, s6
	s_addc_u32 s13, s9, s7
	global_load_dwordx4 v[6:9], v17, s[12:13] offset:16
	global_load_dwordx4 v[10:13], v17, s[12:13]
	s_add_u32 s12, s10, s6
	s_addc_u32 s13, s11, s7
	global_load_dwordx4 v[18:21], v17, s[12:13]
	global_load_dwordx4 v[22:25], v17, s[12:13] offset:16
	s_add_u32 s6, s6, 32
	s_addc_u32 s7, s7, 0
	s_cmpk_eq_i32 s6, 0x100
	s_waitcnt vmcnt(2)
	v_max3_f32 v1, v1, |v10|, |v11|
	v_max3_f32 v1, v1, |v12|, |v13|
	s_waitcnt vmcnt(1)
	v_max3_f32 v0, v0, |v18|, |v19|
	v_max3_f32 v0, v0, |v20|, |v21|
	v_max3_f32 v1, v1, |v6|, |v7|
	s_waitcnt vmcnt(0)
	v_max3_f32 v0, v0, |v22|, |v23|
	v_max3_f32 v1, v1, |v8|, |v9|
	v_max3_f32 v0, v0, |v24|, |v25|
	s_cbranch_scc0 .LBB0_934
	s_mov_b32 s6, s2
	s_cmpk_gt_i32 s6, 0x40f
	s_cbranch_scc1 .LBB0_945
	v_bfe_u32 v2, v4, 5, 1
	v_mul_f32_e32 v1, 0x41000000, v1
	v_lshlrev_b32_e32 v6, 4, v2
	v_mov_b32_e32 v7, v17
	v_mul_f32_e32 v0, v0, v1
	v_lshlrev_b32_e32 v16, 3, v2
	v_lshl_add_u64 v[2:3], s[4:5], 0, v[6:7]
	s_mov_b64 s[8:9], 0x8b28000
	v_lshlrev_b32_e32 v1, 4, v4
	v_lshl_add_u64 v[122:123], v[2:3], 0, s[8:9]
	v_and_b32_e32 v2, 0x70, v1
	v_mov_b32_e32 v3, v17
	v_add_u32_e32 v7, 0x100, v4
	v_lshl_add_u64 v[8:9], s[4:5], 0, v[2:3]
	s_mov_b64 s[8:9], 0xaba8000
	v_ashrrev_i32_e32 v231, 3, v4
	v_ashrrev_i32_e32 v232, 3, v7
	s_movk_i32 s7, 0x48
	v_and_b32_e32 v5, 31, v4
	v_lshl_add_u64 v[124:125], v[8:9], 0, s[8:9]
	s_mov_b64 s[8:9], 0xbbe8000
	v_mul_lo_u32 v233, v231, s7
	v_mul_lo_u32 v235, v232, s7
	s_movk_i32 s7, 0x90
	v_lshl_add_u64 v[126:127], v[8:9], 0, s[8:9]
	v_lshl_add_u64 v[8:9], s[4:5], 0, v[16:17]
	s_mov_b64 s[8:9], 0x6aa8000
	v_mad_u32_u24 v5, v5, s7, 0
	s_add_u32 s7, s4, 0xbbe8080
	v_lshl_add_u64 v[128:129], v[8:9], 0, s[8:9]
	s_addc_u32 s8, s5, 0
	v_mul_f32_e32 v0, 0xbfb8aa3b, v0
	v_and_b32_e32 v121, 0xffffffdf, v4
	v_add_u32_e32 v230, 0, v2
	v_and_b32_e32 v4, 7, v4
	s_add_u32 s9, s4, 0xabb8000
	v_mov_b32_e32 v1, v0
	v_mov_b32_e32 v2, v0
	v_mov_b32_e32 v3, v0
	v_lshl_add_u32 v234, v233, 1, v230
	v_lshl_add_u32 v236, v235, 1, v230
	v_add_u32_e32 v237, v5, v6
	v_add_u32_e32 v238, v5, v16
	v_lshlrev_b32_e32 v16, 4, v4
	s_addc_u32 s10, s5, 0

.LBB0_942:
	s_lshl_b32 s13, s12, 4
	s_lshl_b32 s52, s12, 7
	s_and_b32 s13, s13, 0x7fffffc0
	v_add_u32_e32 v8, s11, v231
	v_lshl_add_u64 v[12:13], v[122:123], 0, s[52:53]
	s_lshl_b32 s52, s13, 1
	v_ashrrev_i32_e32 v9, 31, v8
	v_lshl_add_u64 v[4:5], v[124:125], 0, s[52:53]
	s_lshl_b32 s52, s11, 1
	v_lshlrev_b64 v[68:69], 10, v[8:9]
	v_lshl_add_u64 v[6:7], v[126:127], 0, s[52:53]
	v_lshl_add_u64 v[8:9], v[4:5], 0, v[68:69]
	v_add_u32_e32 v51, s13, v231
	v_mad_i64_i32 v[10:11], s[14:15], v51, s57, v[6:7]
	global_load_dwordx4 v[52:55], v[8:9], off
	global_load_dwordx4 v[56:59], v[10:11], off
	v_add_u32_e32 v8, s11, v232
	v_ashrrev_i32_e32 v9, 31, v8
	v_lshlrev_b64 v[70:71], 10, v[8:9]
	v_lshl_add_u64 v[4:5], v[4:5], 0, v[70:71]
	v_add_u32_e32 v74, s13, v232
	v_mad_i64_i32 v[6:7], s[14:15], v74, s57, v[6:7]
	global_load_dwordx4 v[60:63], v[4:5], off
	global_load_dwordx4 v[64:67], v[6:7], off
	v_add_u32_e32 v152, s4, v121
	v_or_b32_e32 v154, 32, v152
	v_ashrrev_i32_e32 v153, 31, v152
	v_ashrrev_i32_e32 v155, 31, v154
	v_lshlrev_b64 v[152:153], 11, v[152:153]
	v_lshlrev_b64 v[154:155], 11, v[154:155]
	v_lshl_add_u64 v[152:153], v[12:13], 0, v[152:153]
	v_lshl_add_u64 v[154:155], v[12:13], 0, v[154:155]
	global_load_dwordx4 v[18:21], v[152:153], off
	global_load_dwordx4 v[22:25], v[152:153], off offset:32
	global_load_dwordx4 v[26:29], v[152:153], off offset:64
	global_load_dwordx4 v[30:33], v[152:153], off offset:96
	global_load_dwordx4 v[34:37], v[154:155], off
	global_load_dwordx4 v[130:133], v[154:155], off offset:32
	global_load_dwordx4 v[134:137], v[154:155], off offset:64
	global_load_dwordx4 v[248:251], v[154:155], off offset:96
	v_mov_b32_e32 v4, v0
	v_mov_b32_e32 v5, v0
	v_mov_b32_e32 v6, v0
	v_mov_b32_e32 v7, v0
	v_mov_b32_e32 v8, v0
	v_mov_b32_e32 v9, v0
	v_mov_b32_e32 v10, v0
	v_mov_b32_e32 v11, v0
	v_mov_b32_e32 v12, v0
	v_mov_b32_e32 v13, v0
	v_mov_b32_e32 v14, v0
	v_mov_b32_e32 v15, v0
	s_lshl_b32 s11, s5, 6
	s_lshl_b32 s4, s12, 6
	s_add_i32 s11, s11, 64
	s_add_u32 s14, s7, s52
	s_addc_u32 s15, s8, 0
	s_lshl_b32 s12, s12, 5
	v_mov_b64_e32 v[72:73], s[14:15]
	s_and_b32 s14, s12, 0xffffff80
	v_mad_i64_i32 v[138:139], s[12:13], v74, s57, v[72:73]
	v_mad_i64_i32 v[140:141], s[12:13], v51, s57, v[72:73]
	s_add_u32 s12, s9, s14
	v_mov_b32_e32 v38, 0
	s_addc_u32 s13, s10, 0
	s_mov_b32 s5, 0
	v_mov_b32_e32 v39, v38
	v_mov_b32_e32 v40, v38
	v_mov_b32_e32 v41, v38
	v_mov_b32_e32 v42, v38
	v_mov_b32_e32 v43, v38
	v_mov_b32_e32 v44, v38
	v_mov_b32_e32 v45, v38
	v_mov_b32_e32 v46, v38
	v_mov_b32_e32 v47, v38
	v_mov_b32_e32 v48, v38
	v_mov_b32_e32 v49, v38
	v_mov_b32_e32 v50, v38
	v_lshl_add_u64 v[142:143], s[12:13], 0, v[70:71]
	v_lshl_add_u64 v[144:145], s[12:13], 0, v[68:69]
	v_mov_b32_e32 v51, v38
	v_mov_b32_e32 v68, v38
	v_mov_b32_e32 v69, v38
	v_mov_b32_e32 v70, v38
	v_mov_b32_e32 v71, v38
	v_mov_b32_e32 v72, v38
	v_mov_b32_e32 v73, v38
	v_mov_b32_e32 v74, v38
	v_mov_b32_e32 v75, v38
	v_mov_b32_e32 v76, v38
	v_mov_b32_e32 v77, v38
	v_mov_b32_e32 v78, v38
	v_mov_b32_e32 v79, v38
	v_mov_b32_e32 v80, v38
	v_mov_b32_e32 v81, v38
	v_mov_b32_e32 v82, v38
	v_mov_b32_e32 v83, v38
	s_waitcnt vmcnt(11)
	ds_write_b128 v234, v[52:55]
	s_waitcnt vmcnt(10)
	ds_write_b128 v234, v[56:59] offset:18432
	s_waitcnt vmcnt(9)
	ds_write_b128 v236, v[60:63]
	s_waitcnt vmcnt(8)
	ds_write_b128 v236, v[64:67] offset:18432
	v_mov_b32_e32 v52, v38
	v_mov_b32_e32 v53, v38
	v_mov_b32_e32 v54, v38
	v_mov_b32_e32 v55, v38
	v_mov_b32_e32 v56, v38
	v_mov_b32_e32 v57, v38
	v_mov_b32_e32 v58, v38
	v_mov_b32_e32 v59, v38
	v_mov_b32_e32 v60, v38
	v_mov_b32_e32 v61, v38
	v_mov_b32_e32 v62, v38
	v_mov_b32_e32 v63, v38
	v_mov_b32_e32 v64, v38
	v_mov_b32_e32 v65, v38
	v_mov_b32_e32 v66, v38
	v_mov_b32_e32 v67, v38
	v_mov_b32_e32 v84, v38
	v_mov_b32_e32 v85, v38
	v_mov_b32_e32 v86, v38
	v_mov_b32_e32 v87, v38
	v_mov_b32_e32 v88, v38
	v_mov_b32_e32 v89, v38
	v_mov_b32_e32 v90, v38
	v_mov_b32_e32 v91, v38
	v_mov_b32_e32 v92, v38
	v_mov_b32_e32 v93, v38
	v_mov_b32_e32 v94, v38
	v_mov_b32_e32 v95, v38
	v_mov_b32_e32 v96, v38
	v_mov_b32_e32 v97, v38
	v_mov_b32_e32 v98, v38
	v_mov_b32_e32 v99, v38
	v_mov_b32_e32 v100, v38
	v_mov_b32_e32 v101, v38
	v_mov_b32_e32 v146, v38
	v_mov_b32_e32 v147, v38
	v_mov_b32_e32 v148, v38
	v_mov_b32_e32 v149, v38
	s_waitcnt lgkmcnt(0)
	s_barrier
.LBB0_943:
	s_and_b32 s12, s5, 64
	s_mulk_i32 s12, 0x90
	v_add_u32_e32 v148, s12, v237
	ds_read_b128 v[192:195], v148
	ds_read_b128 v[196:199], v148 offset:32
	ds_read_b128 v[200:203], v148 offset:64
	ds_read_b128 v[204:207], v148 offset:96
	s_addk_i32 s12, 0x4800
	v_add_u32_e32 v149, s12, v238
	s_addk_i32 s12, 0x1200
	v_add_u32_e32 v150, s12, v238
	v_lshl_add_u64 v[102:103], v[144:145], 0, v[16:17]
	global_load_dwordx4 v[102:105], v[102:103], off
	v_lshl_add_u64 v[106:107], v[140:141], 0, v[16:17]
	global_load_dwordx4 v[106:109], v[106:107], off
	v_lshl_add_u64 v[110:111], v[142:143], 0, v[16:17]
	global_load_dwordx4 v[110:113], v[110:111], off
	v_lshl_add_u64 v[114:115], v[138:139], 0, v[16:17]
	global_load_dwordx4 v[114:117], v[114:115], off
	s_waitcnt vmcnt(4)
	s_add_i32 s5, s5, 64
	s_waitcnt lgkmcnt(3)
	v_mfma_f32_32x32x16_bf16 v[152:167], v[192:195], v[18:21], v[0:15]
	ds_read2_b64 v[212:215], v149 offset1:2
	s_waitcnt lgkmcnt(3)
	v_mfma_f32_32x32x16_bf16 v[152:167], v[196:199], v[22:25], v[152:167]
	ds_read2_b64 v[220:223], v150 offset1:2
	s_waitcnt lgkmcnt(3)
	v_mfma_f32_32x32x16_bf16 v[152:167], v[200:203], v[26:29], v[152:167]
	ds_read2_b64 v[216:219], v149 offset0:4 offset1:6
	s_waitcnt lgkmcnt(3)
	v_mfma_f32_32x32x16_bf16 v[152:167], v[204:207], v[30:33], v[152:167]
	ds_read2_b64 v[244:247], v150 offset0:4 offset1:6
	v_lshl_add_u64 v[138:139], v[138:139], 0, s[66:67]
	v_lshl_add_u64 v[140:141], v[140:141], 0, s[66:67]
	v_lshl_add_u64 v[142:143], v[142:143], 0, s[68:69]
	v_lshl_add_u64 v[144:145], v[144:145], 0, s[68:69]
	v_mfma_f32_32x32x16_bf16 v[168:183], v[192:195], v[34:37], v[0:15]
	ds_read_b128 v[192:195], v148 offset:4608
	v_mfma_f32_32x32x16_bf16 v[168:183], v[196:199], v[130:133], v[168:183]
	ds_read_b128 v[196:199], v148 offset:4640
	v_mfma_f32_32x32x16_bf16 v[168:183], v[200:203], v[134:137], v[168:183]
	ds_read_b128 v[200:203], v148 offset:4672
	v_mfma_f32_32x32x16_bf16 v[168:183], v[204:207], v[248:251], v[168:183]
	ds_read_b128 v[204:207], v148 offset:4704
	v_exp_f32_e32 v152, v152
	v_exp_f32_e32 v153, v153
	v_exp_f32_e32 v154, v154
	v_exp_f32_e32 v155, v155
	v_exp_f32_e32 v156, v156
	v_exp_f32_e32 v157, v157
	v_exp_f32_e32 v158, v158
	v_exp_f32_e32 v159, v159
	v_exp_f32_e32 v160, v160
	v_exp_f32_e32 v161, v161
	v_exp_f32_e32 v162, v162
	v_exp_f32_e32 v163, v163
	v_exp_f32_e32 v164, v164
	v_exp_f32_e32 v165, v165
	v_exp_f32_e32 v166, v166
	v_exp_f32_e32 v167, v167
	v_cvt_pk_bf16_f32 v184, v152, v153
	v_cvt_pk_bf16_f32 v185, v154, v155
	v_cvt_pk_bf16_f32 v186, v156, v157
	v_cvt_pk_bf16_f32 v187, v158, v159
	v_cvt_pk_bf16_f32 v188, v160, v161
	v_cvt_pk_bf16_f32 v189, v162, v163
	v_cvt_pk_bf16_f32 v190, v164, v165
	v_cvt_pk_bf16_f32 v191, v166, v167
	v_add_f32_e32 v152, v152, v153
	v_add_f32_e32 v154, v154, v155
	v_add_f32_e32 v156, v156, v157
	v_add_f32_e32 v158, v158, v159
	v_add_f32_e32 v160, v160, v161
	v_add_f32_e32 v162, v162, v163
	v_add_f32_e32 v164, v164, v165
	v_add_f32_e32 v166, v166, v167
	v_add_f32_e32 v152, v152, v154
	v_add_f32_e32 v156, v156, v158
	v_add_f32_e32 v160, v160, v162
	v_add_f32_e32 v164, v164, v166
	v_add_f32_e32 v152, v152, v156
	v_add_f32_e32 v160, v160, v164
	v_add_f32_e32 v152, v152, v160
	v_add_f32_e32 v146, v146, v152
	s_waitcnt lgkmcnt(7)
	v_mfma_f32_32x32x16_bf16 v[38:53], v[212:215], v[184:187], v[38:53]
	v_exp_f32_e32 v168, v168
	v_exp_f32_e32 v169, v169
	v_exp_f32_e32 v170, v170
	v_exp_f32_e32 v171, v171
	s_waitcnt lgkmcnt(6)
	v_mfma_f32_32x32x16_bf16 v[70:85], v[220:223], v[184:187], v[70:85]
	v_exp_f32_e32 v172, v172
	v_exp_f32_e32 v173, v173
	v_exp_f32_e32 v174, v174
	v_exp_f32_e32 v175, v175
	s_waitcnt lgkmcnt(5)
	v_mfma_f32_32x32x16_bf16 v[38:53], v[216:219], v[188:191], v[38:53]
	v_exp_f32_e32 v176, v176
	v_exp_f32_e32 v177, v177
	v_exp_f32_e32 v178, v178
	v_exp_f32_e32 v179, v179
	s_waitcnt lgkmcnt(4)
	v_mfma_f32_32x32x16_bf16 v[70:85], v[244:247], v[188:191], v[70:85]
	v_exp_f32_e32 v180, v180
	v_exp_f32_e32 v181, v181
	v_exp_f32_e32 v182, v182
	v_exp_f32_e32 v183, v183
	v_cvt_pk_bf16_f32 v184, v168, v169
	s_waitcnt lgkmcnt(3)
	v_mfma_f32_32x32x16_bf16 v[152:167], v[192:195], v[18:21], v[0:15]
	v_cvt_pk_bf16_f32 v185, v170, v171
	v_cvt_pk_bf16_f32 v186, v172, v173
	v_cvt_pk_bf16_f32 v187, v174, v175
	v_cvt_pk_bf16_f32 v188, v176, v177
	s_waitcnt lgkmcnt(2)
	v_mfma_f32_32x32x16_bf16 v[152:167], v[196:199], v[22:25], v[152:167]
	v_cvt_pk_bf16_f32 v189, v178, v179
	v_cvt_pk_bf16_f32 v190, v180, v181
	v_cvt_pk_bf16_f32 v191, v182, v183
	v_add_f32_e32 v168, v168, v169
	s_waitcnt lgkmcnt(1)
	v_mfma_f32_32x32x16_bf16 v[152:167], v[200:203], v[26:29], v[152:167]
	v_add_f32_e32 v170, v170, v171
	v_add_f32_e32 v172, v172, v173
	v_add_f32_e32 v174, v174, v175
	v_add_f32_e32 v176, v176, v177
	s_waitcnt lgkmcnt(0)
	v_mfma_f32_32x32x16_bf16 v[152:167], v[204:207], v[30:33], v[152:167]
	v_add_f32_e32 v178, v178, v179
	v_add_f32_e32 v180, v180, v181
	v_add_f32_e32 v182, v182, v183
	v_add_f32_e32 v168, v168, v170
	v_add_f32_e32 v172, v172, v174
	v_add_f32_e32 v176, v176, v178
	v_add_f32_e32 v180, v180, v182
	v_add_f32_e32 v168, v168, v172
	v_add_f32_e32 v176, v176, v180
	v_add_f32_e32 v168, v168, v176
	v_add_f32_e32 v147, v147, v168
	v_mfma_f32_32x32x16_bf16 v[54:69], v[212:215], v[184:187], v[54:69]
	ds_read2_b64 v[212:215], v149 offset0:8 offset1:10
	v_exp_f32_e32 v152, v152
	v_exp_f32_e32 v153, v153
	v_exp_f32_e32 v154, v154
	v_exp_f32_e32 v155, v155
	v_mfma_f32_32x32x16_bf16 v[86:101], v[220:223], v[184:187], v[86:101]
	ds_read2_b64 v[220:223], v150 offset0:8 offset1:10
	v_exp_f32_e32 v156, v156
	v_exp_f32_e32 v157, v157
	v_exp_f32_e32 v158, v158
	v_exp_f32_e32 v159, v159
	v_mfma_f32_32x32x16_bf16 v[54:69], v[216:219], v[188:191], v[54:69]
	ds_read2_b64 v[216:219], v149 offset0:12 offset1:14
	v_exp_f32_e32 v160, v160
	v_exp_f32_e32 v161, v161
	v_exp_f32_e32 v162, v162
	v_exp_f32_e32 v163, v163
	v_mfma_f32_32x32x16_bf16 v[86:101], v[244:247], v[188:191], v[86:101]
	ds_read2_b64 v[244:247], v150 offset0:12 offset1:14
	v_exp_f32_e32 v164, v164
	v_exp_f32_e32 v165, v165
	v_exp_f32_e32 v166, v166
	v_exp_f32_e32 v167, v167
	v_cvt_pk_bf16_f32 v184, v152, v153
	v_mfma_f32_32x32x16_bf16 v[168:183], v[192:195], v[34:37], v[0:15]
	v_cvt_pk_bf16_f32 v185, v154, v155
	v_cvt_pk_bf16_f32 v186, v156, v157
	v_cvt_pk_bf16_f32 v187, v158, v159
	v_cvt_pk_bf16_f32 v188, v160, v161
	v_mfma_f32_32x32x16_bf16 v[168:183], v[196:199], v[130:133], v[168:183]
	v_cvt_pk_bf16_f32 v189, v162, v163
	v_cvt_pk_bf16_f32 v190, v164, v165
	v_cvt_pk_bf16_f32 v191, v166, v167
	v_add_f32_e32 v152, v152, v153
	v_mfma_f32_32x32x16_bf16 v[168:183], v[200:203], v[134:137], v[168:183]
	v_add_f32_e32 v154, v154, v155
	v_add_f32_e32 v156, v156, v157
	v_add_f32_e32 v158, v158, v159
	v_add_f32_e32 v160, v160, v161
	v_mfma_f32_32x32x16_bf16 v[168:183], v[204:207], v[248:251], v[168:183]
	v_add_f32_e32 v162, v162, v163
	v_add_f32_e32 v164, v164, v165
	v_add_f32_e32 v166, v166, v167
	v_add_f32_e32 v152, v152, v154
	v_add_f32_e32 v156, v156, v158
	v_add_f32_e32 v160, v160, v162
	v_add_f32_e32 v164, v164, v166
	v_add_f32_e32 v152, v152, v156
	v_add_f32_e32 v160, v160, v164
	v_add_f32_e32 v152, v152, v160
	v_add_f32_e32 v146, v146, v152
	s_waitcnt lgkmcnt(3)
	v_mfma_f32_32x32x16_bf16 v[38:53], v[212:215], v[184:187], v[38:53]
	v_exp_f32_e32 v168, v168
	v_exp_f32_e32 v169, v169
	v_exp_f32_e32 v170, v170
	v_exp_f32_e32 v171, v171
	s_waitcnt lgkmcnt(2)
	v_mfma_f32_32x32x16_bf16 v[70:85], v[220:223], v[184:187], v[70:85]
	v_exp_f32_e32 v172, v172
	v_exp_f32_e32 v173, v173
	v_exp_f32_e32 v174, v174
	v_exp_f32_e32 v175, v175
	s_waitcnt lgkmcnt(1)
	v_mfma_f32_32x32x16_bf16 v[38:53], v[216:219], v[188:191], v[38:53]
	v_exp_f32_e32 v176, v176
	v_exp_f32_e32 v177, v177
	v_exp_f32_e32 v178, v178
	v_exp_f32_e32 v179, v179
	s_waitcnt lgkmcnt(0)
	v_mfma_f32_32x32x16_bf16 v[70:85], v[244:247], v[188:191], v[70:85]
	v_exp_f32_e32 v180, v180
	v_exp_f32_e32 v181, v181
	v_exp_f32_e32 v182, v182
	v_exp_f32_e32 v183, v183
	v_cvt_pk_bf16_f32 v184, v168, v169
	v_cvt_pk_bf16_f32 v185, v170, v171
	v_cvt_pk_bf16_f32 v186, v172, v173
	v_cvt_pk_bf16_f32 v187, v174, v175
	v_cvt_pk_bf16_f32 v188, v176, v177
	v_cvt_pk_bf16_f32 v189, v178, v179
	v_cvt_pk_bf16_f32 v190, v180, v181
	v_cvt_pk_bf16_f32 v191, v182, v183
	v_add_f32_e32 v168, v168, v169
	v_add_f32_e32 v170, v170, v171
	v_add_f32_e32 v172, v172, v173
	v_add_f32_e32 v174, v174, v175
	v_add_f32_e32 v176, v176, v177
	v_add_f32_e32 v178, v178, v179
	v_add_f32_e32 v180, v180, v181
	v_add_f32_e32 v182, v182, v183
	v_add_f32_e32 v168, v168, v170
	v_add_f32_e32 v172, v172, v174
	v_add_f32_e32 v176, v176, v178
	v_add_f32_e32 v180, v180, v182
	v_add_f32_e32 v168, v168, v172
	v_add_f32_e32 v176, v176, v180
	v_add_f32_e32 v168, v168, v176
	v_add_f32_e32 v147, v147, v168
	v_mfma_f32_32x32x16_bf16 v[54:69], v[212:215], v[184:187], v[54:69]
	s_and_b32 s12, s5, 64
	s_mulk_i32 s12, 0x90
	v_add_u32_e32 v192, s12, v230
	v_mfma_f32_32x32x16_bf16 v[86:101], v[220:223], v[184:187], v[86:101]
	v_lshl_add_u32 v193, v233, 1, v192
	v_lshl_add_u32 v194, v235, 1, v192
	s_waitcnt vmcnt(3)
	ds_write_b128 v193, v[102:105]
	v_mfma_f32_32x32x16_bf16 v[54:69], v[216:219], v[188:191], v[54:69]
	s_waitcnt vmcnt(2)
	ds_write_b128 v193, v[106:109] offset:18432
	s_waitcnt vmcnt(1)
	v_mfma_f32_32x32x16_bf16 v[86:101], v[244:247], v[188:191], v[86:101]
	ds_write_b128 v194, v[110:113]
	s_waitcnt vmcnt(0)
	ds_write_b128 v194, v[114:117] offset:18432
	s_cmp_eq_u32 s11, s5
	s_waitcnt lgkmcnt(0)
	s_barrier
	s_cbranch_scc0 .LBB0_943
	s_movk_i32 s12, 0x2400
	v_add_u32_e32 v148, s12, v237
	ds_read_b128 v[192:195], v148
	ds_read_b128 v[196:199], v148 offset:32
	ds_read_b128 v[200:203], v148 offset:64
	ds_read_b128 v[204:207], v148 offset:96
	s_addk_i32 s12, 0x4800
	v_add_u32_e32 v149, s12, v238
	s_addk_i32 s12, 0x1200
	v_add_u32_e32 v150, s12, v238
	s_waitcnt vmcnt(0)
	s_waitcnt lgkmcnt(3)
	v_mfma_f32_32x32x16_bf16 v[152:167], v[192:195], v[18:21], v[0:15]
	ds_read2_b64 v[212:215], v149 offset1:2
	s_waitcnt lgkmcnt(3)
	v_mfma_f32_32x32x16_bf16 v[152:167], v[196:199], v[22:25], v[152:167]
	ds_read2_b64 v[220:223], v150 offset1:2
	s_waitcnt lgkmcnt(3)
	v_mfma_f32_32x32x16_bf16 v[152:167], v[200:203], v[26:29], v[152:167]
	ds_read2_b64 v[216:219], v149 offset0:4 offset1:6
	s_waitcnt lgkmcnt(3)
	v_mfma_f32_32x32x16_bf16 v[152:167], v[204:207], v[30:33], v[152:167]
	ds_read2_b64 v[244:247], v150 offset0:4 offset1:6
	v_mfma_f32_32x32x16_bf16 v[168:183], v[192:195], v[34:37], v[0:15]
	ds_read_b128 v[192:195], v148 offset:4608
	v_mfma_f32_32x32x16_bf16 v[168:183], v[196:199], v[130:133], v[168:183]
	ds_read_b128 v[196:199], v148 offset:4640
	v_mfma_f32_32x32x16_bf16 v[168:183], v[200:203], v[134:137], v[168:183]
	ds_read_b128 v[200:203], v148 offset:4672
	v_mfma_f32_32x32x16_bf16 v[168:183], v[204:207], v[248:251], v[168:183]
	ds_read_b128 v[204:207], v148 offset:4704
	s_nop 0
	s_nop 0
	s_nop 0
	v_exp_f32_e32 v152, v152
	v_exp_f32_e32 v153, v153
	v_exp_f32_e32 v154, v154
	v_exp_f32_e32 v155, v155
	v_exp_f32_e32 v156, v156
	v_exp_f32_e32 v157, v157
	v_exp_f32_e32 v158, v158
	v_exp_f32_e32 v159, v159
	v_exp_f32_e32 v160, v160
	v_exp_f32_e32 v161, v161
	v_exp_f32_e32 v162, v162
	v_exp_f32_e32 v163, v163
	v_exp_f32_e32 v164, v164
	v_exp_f32_e32 v165, v165
	v_exp_f32_e32 v166, v166
	v_exp_f32_e32 v167, v167
	v_cvt_pk_bf16_f32 v184, v152, v153
	v_cvt_pk_bf16_f32 v185, v154, v155
	v_cvt_pk_bf16_f32 v186, v156, v157
	v_cvt_pk_bf16_f32 v187, v158, v159
	v_cvt_pk_bf16_f32 v188, v160, v161
	v_cvt_pk_bf16_f32 v189, v162, v163
	v_cvt_pk_bf16_f32 v190, v164, v165
	v_cvt_pk_bf16_f32 v191, v166, v167
	v_add_f32_e32 v152, v152, v153
	v_add_f32_e32 v154, v154, v155
	v_add_f32_e32 v156, v156, v157
	v_add_f32_e32 v158, v158, v159
	v_add_f32_e32 v160, v160, v161
	v_add_f32_e32 v162, v162, v163
	v_add_f32_e32 v164, v164, v165
	v_add_f32_e32 v166, v166, v167
	v_add_f32_e32 v152, v152, v154
	v_add_f32_e32 v156, v156, v158
	v_add_f32_e32 v160, v160, v162
	v_add_f32_e32 v164, v164, v166
	v_add_f32_e32 v152, v152, v156
	v_add_f32_e32 v160, v160, v164
	v_add_f32_e32 v152, v152, v160
	v_add_f32_e32 v146, v146, v152
	s_waitcnt lgkmcnt(7)
	v_mfma_f32_32x32x16_bf16 v[38:53], v[212:215], v[184:187], v[38:53]
	v_exp_f32_e32 v168, v168
	v_exp_f32_e32 v169, v169
	v_exp_f32_e32 v170, v170
	v_exp_f32_e32 v171, v171
	s_waitcnt lgkmcnt(6)
	v_mfma_f32_32x32x16_bf16 v[70:85], v[220:223], v[184:187], v[70:85]
	v_exp_f32_e32 v172, v172
	v_exp_f32_e32 v173, v173
	v_exp_f32_e32 v174, v174
	v_exp_f32_e32 v175, v175
	s_waitcnt lgkmcnt(5)
	v_mfma_f32_32x32x16_bf16 v[38:53], v[216:219], v[188:191], v[38:53]
	v_exp_f32_e32 v176, v176
	v_exp_f32_e32 v177, v177
	v_exp_f32_e32 v178, v178
	v_exp_f32_e32 v179, v179
	s_waitcnt lgkmcnt(4)
	v_mfma_f32_32x32x16_bf16 v[70:85], v[244:247], v[188:191], v[70:85]
	v_exp_f32_e32 v180, v180
	v_exp_f32_e32 v181, v181
	v_exp_f32_e32 v182, v182
	v_exp_f32_e32 v183, v183
	v_cvt_pk_bf16_f32 v184, v168, v169
	s_waitcnt lgkmcnt(3)
	v_mfma_f32_32x32x16_bf16 v[152:167], v[192:195], v[18:21], v[0:15]
	v_cvt_pk_bf16_f32 v185, v170, v171
	v_cvt_pk_bf16_f32 v186, v172, v173
	v_cvt_pk_bf16_f32 v187, v174, v175
	v_cvt_pk_bf16_f32 v188, v176, v177
	s_waitcnt lgkmcnt(2)
	v_mfma_f32_32x32x16_bf16 v[152:167], v[196:199], v[22:25], v[152:167]
	v_cvt_pk_bf16_f32 v189, v178, v179
	v_cvt_pk_bf16_f32 v190, v180, v181
	v_cvt_pk_bf16_f32 v191, v182, v183
	v_add_f32_e32 v168, v168, v169
	s_waitcnt lgkmcnt(1)
	v_mfma_f32_32x32x16_bf16 v[152:167], v[200:203], v[26:29], v[152:167]
	v_add_f32_e32 v170, v170, v171
	v_add_f32_e32 v172, v172, v173
	v_add_f32_e32 v174, v174, v175
	v_add_f32_e32 v176, v176, v177
	s_waitcnt lgkmcnt(0)
	v_mfma_f32_32x32x16_bf16 v[152:167], v[204:207], v[30:33], v[152:167]
	v_add_f32_e32 v178, v178, v179
	v_add_f32_e32 v180, v180, v181
	v_add_f32_e32 v182, v182, v183
	v_add_f32_e32 v168, v168, v170
	v_add_f32_e32 v172, v172, v174
	v_add_f32_e32 v176, v176, v178
	v_add_f32_e32 v180, v180, v182
	v_add_f32_e32 v168, v168, v172
	v_add_f32_e32 v176, v176, v180
	v_add_f32_e32 v168, v168, v176
	v_add_f32_e32 v147, v147, v168
	v_mfma_f32_32x32x16_bf16 v[54:69], v[212:215], v[184:187], v[54:69]
	ds_read2_b64 v[212:215], v149 offset0:8 offset1:10
	v_exp_f32_e32 v152, v152
	v_exp_f32_e32 v153, v153
	v_exp_f32_e32 v154, v154
	v_exp_f32_e32 v155, v155
	v_mfma_f32_32x32x16_bf16 v[86:101], v[220:223], v[184:187], v[86:101]
	ds_read2_b64 v[220:223], v150 offset0:8 offset1:10
	v_exp_f32_e32 v156, v156
	v_exp_f32_e32 v157, v157
	v_exp_f32_e32 v158, v158
	v_exp_f32_e32 v159, v159
	v_mfma_f32_32x32x16_bf16 v[54:69], v[216:219], v[188:191], v[54:69]
	ds_read2_b64 v[216:219], v149 offset0:12 offset1:14
	v_exp_f32_e32 v160, v160
	v_exp_f32_e32 v161, v161
	v_exp_f32_e32 v162, v162
	v_exp_f32_e32 v163, v163
	v_mfma_f32_32x32x16_bf16 v[86:101], v[244:247], v[188:191], v[86:101]
	ds_read2_b64 v[244:247], v150 offset0:12 offset1:14
	v_exp_f32_e32 v164, v164
	v_exp_f32_e32 v165, v165
	v_exp_f32_e32 v166, v166
	v_exp_f32_e32 v167, v167
	v_cvt_pk_bf16_f32 v184, v152, v153
	v_mfma_f32_32x32x16_bf16 v[168:183], v[192:195], v[34:37], v[0:15]
	v_cvt_pk_bf16_f32 v185, v154, v155
	v_cvt_pk_bf16_f32 v186, v156, v157
	v_cvt_pk_bf16_f32 v187, v158, v159
	v_cvt_pk_bf16_f32 v188, v160, v161
	v_mfma_f32_32x32x16_bf16 v[168:183], v[196:199], v[130:133], v[168:183]
	v_cvt_pk_bf16_f32 v189, v162, v163
	v_cvt_pk_bf16_f32 v190, v164, v165
	v_cvt_pk_bf16_f32 v191, v166, v167
	v_add_f32_e32 v152, v152, v153
	v_mfma_f32_32x32x16_bf16 v[168:183], v[200:203], v[134:137], v[168:183]
	v_add_f32_e32 v154, v154, v155
	v_add_f32_e32 v156, v156, v157
	v_add_f32_e32 v158, v158, v159
	v_add_f32_e32 v160, v160, v161
	v_mfma_f32_32x32x16_bf16 v[168:183], v[204:207], v[248:251], v[168:183]
	v_add_f32_e32 v162, v162, v163
	v_add_f32_e32 v164, v164, v165
	v_add_f32_e32 v166, v166, v167
	v_add_f32_e32 v152, v152, v154
	v_add_f32_e32 v156, v156, v158
	v_add_f32_e32 v160, v160, v162
	v_add_f32_e32 v164, v164, v166
	v_add_f32_e32 v152, v152, v156
	v_add_f32_e32 v160, v160, v164
	v_add_f32_e32 v152, v152, v160
	v_add_f32_e32 v146, v146, v152
	s_waitcnt lgkmcnt(3)
	v_mfma_f32_32x32x16_bf16 v[38:53], v[212:215], v[184:187], v[38:53]
	v_exp_f32_e32 v168, v168
	v_exp_f32_e32 v169, v169
	v_exp_f32_e32 v170, v170
	v_exp_f32_e32 v171, v171
	s_waitcnt lgkmcnt(2)
	v_mfma_f32_32x32x16_bf16 v[70:85], v[220:223], v[184:187], v[70:85]
	v_exp_f32_e32 v172, v172
	v_exp_f32_e32 v173, v173
	v_exp_f32_e32 v174, v174
	v_exp_f32_e32 v175, v175
	s_waitcnt lgkmcnt(1)
	v_mfma_f32_32x32x16_bf16 v[38:53], v[216:219], v[188:191], v[38:53]
	v_exp_f32_e32 v176, v176
	v_exp_f32_e32 v177, v177
	v_exp_f32_e32 v178, v178
	v_exp_f32_e32 v179, v179
	s_waitcnt lgkmcnt(0)
	v_mfma_f32_32x32x16_bf16 v[70:85], v[244:247], v[188:191], v[70:85]
	v_exp_f32_e32 v180, v180
	v_exp_f32_e32 v181, v181
	v_exp_f32_e32 v182, v182
	v_exp_f32_e32 v183, v183
	v_cvt_pk_bf16_f32 v184, v168, v169
	v_cvt_pk_bf16_f32 v185, v170, v171
	v_cvt_pk_bf16_f32 v186, v172, v173
	v_cvt_pk_bf16_f32 v187, v174, v175
	v_cvt_pk_bf16_f32 v188, v176, v177
	v_cvt_pk_bf16_f32 v189, v178, v179
	v_cvt_pk_bf16_f32 v190, v180, v181
	v_cvt_pk_bf16_f32 v191, v182, v183
	v_add_f32_e32 v168, v168, v169
	v_add_f32_e32 v170, v170, v171
	v_add_f32_e32 v172, v172, v173
	v_add_f32_e32 v174, v174, v175
	v_add_f32_e32 v176, v176, v177
	v_add_f32_e32 v178, v178, v179
	v_add_f32_e32 v180, v180, v181
	v_add_f32_e32 v182, v182, v183
	v_add_f32_e32 v168, v168, v170
	v_add_f32_e32 v172, v172, v174
	v_add_f32_e32 v176, v176, v178
	v_add_f32_e32 v180, v180, v182
	v_add_f32_e32 v168, v168, v172
	v_add_f32_e32 v176, v176, v180
	v_add_f32_e32 v168, v168, v176
	v_add_f32_e32 v147, v147, v168
	v_mfma_f32_32x32x16_bf16 v[54:69], v[212:215], v[184:187], v[54:69]
	v_mfma_f32_32x32x16_bf16 v[86:101], v[220:223], v[184:187], v[86:101]
	v_mfma_f32_32x32x16_bf16 v[54:69], v[216:219], v[188:191], v[54:69]
	v_mfma_f32_32x32x16_bf16 v[86:101], v[244:247], v[188:191], v[86:101]
	s_lshr_b32 s13, s6, 4
	s_lshl_b32 s13, s13, 8
	s_cmpk_lt_u32 s6, 0x400
	s_cselect_b32 s13, s13, 0x4000
	s_add_i32 s6, s6, s3
	s_lshl_b32 s52, s4, 1
	s_barrier
	v_add_u32_e32 v152, s13, v121
	v_or_b32_e32 v154, 32, v152
	v_ashrrev_i32_e32 v153, 31, v152
	v_ashrrev_i32_e32 v155, 31, v154
	v_lshlrev_b64 v[152:153], 11, v[152:153]
	v_lshlrev_b64 v[154:155], 11, v[154:155]
	v_lshl_add_u64 v[156:157], v[128:129], 0, s[52:53]
	v_lshl_add_u64 v[152:153], v[156:157], 0, v[152:153]
	v_lshl_add_u64 v[154:155], v[156:157], 0, v[154:155]
	global_load_dwordx2 v[160:161], v[152:153], off
	global_load_dwordx2 v[162:163], v[152:153], off offset:16
	global_load_dwordx2 v[164:165], v[152:153], off offset:32
	global_load_dwordx2 v[166:167], v[152:153], off offset:48
	global_load_dwordx2 v[168:169], v[152:153], off offset:64
	global_load_dwordx2 v[170:171], v[152:153], off offset:80
	global_load_dwordx2 v[172:173], v[152:153], off offset:96
	global_load_dwordx2 v[174:175], v[152:153], off offset:112
	global_load_dwordx2 v[176:177], v[154:155], off
	global_load_dwordx2 v[178:179], v[154:155], off offset:16
	global_load_dwordx2 v[180:181], v[154:155], off offset:32
	global_load_dwordx2 v[182:183], v[154:155], off offset:48
	global_load_dwordx2 v[184:185], v[154:155], off offset:64
	global_load_dwordx2 v[186:187], v[154:155], off offset:80
	global_load_dwordx2 v[188:189], v[154:155], off offset:96
	global_load_dwordx2 v[190:191], v[154:155], off offset:112
	v_mov_b32_e32 v194, v146
	s_nop 1
	v_permlane32_swap_b32_e32 v194, v146
	s_nop 1
	v_add_f32_e32 v196, v194, v146
	v_div_scale_f32 v198, s[14:15], v196, v196, 1.0
	v_rcp_f32_e32 v199, v198
	v_div_scale_f32 v200, vcc, 1.0, v196, 1.0
	v_fma_f32 v201, -v198, v199, 1.0
	v_fmac_f32_e32 v199, v201, v199
	v_mul_f32_e32 v202, v200, v199
	v_fma_f32 v203, -v198, v202, v200
	v_fmac_f32_e32 v202, v203, v199
	v_fma_f32 v198, -v198, v202, v200
	v_div_fmas_f32 v203, v198, v199, v202
	v_div_fixup_f32 v192, v203, v196, 1.0
	v_mov_b32_e32 v194, v147
	s_nop 1
	v_permlane32_swap_b32_e32 v194, v147
	s_nop 1
	v_add_f32_e32 v197, v194, v147
	v_div_scale_f32 v198, s[14:15], v197, v197, 1.0
	v_rcp_f32_e32 v199, v198
	v_div_scale_f32 v200, vcc, 1.0, v197, 1.0
	v_fma_f32 v201, -v198, v199, 1.0
	v_fmac_f32_e32 v199, v201, v199
	v_mul_f32_e32 v202, v200, v199
	v_fma_f32 v203, -v198, v202, v200
	v_fmac_f32_e32 v202, v203, v199
	v_fma_f32 v198, -v198, v202, v200
	v_div_fmas_f32 v203, v198, v199, v202
	v_div_fixup_f32 v193, v203, v197, 1.0
	s_waitcnt vmcnt(0)
	v_lshlrev_b32_e32 v204, 16, v160
	v_and_b32_e32 v205, 0xffff0000, v160
	v_lshlrev_b32_e32 v206, 16, v161
	v_and_b32_e32 v207, 0xffff0000, v161
	v_mul_f32_e32 v212, 0xbfb8aa3b, v204
	v_mul_f32_e32 v213, 0xbfb8aa3b, v205
	v_mul_f32_e32 v214, 0xbfb8aa3b, v206
	v_mul_f32_e32 v215, 0xbfb8aa3b, v207
	v_exp_f32_e32 v212, v212
	v_exp_f32_e32 v213, v213
	v_exp_f32_e32 v214, v214
	v_exp_f32_e32 v215, v215
	v_mul_f32_e32 v38, v38, v192
	v_mul_f32_e32 v39, v39, v192
	v_mul_f32_e32 v40, v40, v192
	v_mul_f32_e32 v41, v41, v192
	v_add_f32_e32 v212, 1.0, v212
	v_add_f32_e32 v213, 1.0, v213
	v_add_f32_e32 v214, 1.0, v214
	v_add_f32_e32 v215, 1.0, v215
	v_rcp_f32_e32 v212, v212
	v_rcp_f32_e32 v213, v213
	v_rcp_f32_e32 v214, v214
	v_rcp_f32_e32 v215, v215
	s_nop 0
	v_mul_f32_e32 v204, v204, v212
	v_mul_f32_e32 v205, v205, v213
	v_mul_f32_e32 v206, v206, v214
	v_mul_f32_e32 v207, v207, v215
	v_mul_f32_e32 v38, v38, v204
	v_mul_f32_e32 v39, v39, v205
	v_mul_f32_e32 v40, v40, v206
	v_mul_f32_e32 v41, v41, v207
	v_cvt_pk_bf16_f32 v160, v38, v39
	v_cvt_pk_bf16_f32 v161, v40, v41
	global_store_dwordx2 v[152:153], v[160:161], off
	v_lshlrev_b32_e32 v204, 16, v162
	v_and_b32_e32 v205, 0xffff0000, v162
	v_lshlrev_b32_e32 v206, 16, v163
	v_and_b32_e32 v207, 0xffff0000, v163
	v_mul_f32_e32 v212, 0xbfb8aa3b, v204
	v_mul_f32_e32 v213, 0xbfb8aa3b, v205
	v_mul_f32_e32 v214, 0xbfb8aa3b, v206
	v_mul_f32_e32 v215, 0xbfb8aa3b, v207
	v_exp_f32_e32 v212, v212
	v_exp_f32_e32 v213, v213
	v_exp_f32_e32 v214, v214
	v_exp_f32_e32 v215, v215
	v_mul_f32_e32 v42, v42, v192
	v_mul_f32_e32 v43, v43, v192
	v_mul_f32_e32 v44, v44, v192
	v_mul_f32_e32 v45, v45, v192
	v_add_f32_e32 v212, 1.0, v212
	v_add_f32_e32 v213, 1.0, v213
	v_add_f32_e32 v214, 1.0, v214
	v_add_f32_e32 v215, 1.0, v215
	v_rcp_f32_e32 v212, v212
	v_rcp_f32_e32 v213, v213
	v_rcp_f32_e32 v214, v214
	v_rcp_f32_e32 v215, v215
	s_nop 0
	v_mul_f32_e32 v204, v204, v212
	v_mul_f32_e32 v205, v205, v213
	v_mul_f32_e32 v206, v206, v214
	v_mul_f32_e32 v207, v207, v215
	v_mul_f32_e32 v42, v42, v204
	v_mul_f32_e32 v43, v43, v205
	v_mul_f32_e32 v44, v44, v206
	v_mul_f32_e32 v45, v45, v207
	v_cvt_pk_bf16_f32 v162, v42, v43
	v_cvt_pk_bf16_f32 v163, v44, v45
	global_store_dwordx2 v[152:153], v[162:163], off offset:16
	v_lshlrev_b32_e32 v204, 16, v164
	v_and_b32_e32 v205, 0xffff0000, v164
	v_lshlrev_b32_e32 v206, 16, v165
	v_and_b32_e32 v207, 0xffff0000, v165
	v_mul_f32_e32 v212, 0xbfb8aa3b, v204
	v_mul_f32_e32 v213, 0xbfb8aa3b, v205
	v_mul_f32_e32 v214, 0xbfb8aa3b, v206
	v_mul_f32_e32 v215, 0xbfb8aa3b, v207
	v_exp_f32_e32 v212, v212
	v_exp_f32_e32 v213, v213
	v_exp_f32_e32 v214, v214
	v_exp_f32_e32 v215, v215
	v_mul_f32_e32 v46, v46, v192
	v_mul_f32_e32 v47, v47, v192
	v_mul_f32_e32 v48, v48, v192
	v_mul_f32_e32 v49, v49, v192
	v_add_f32_e32 v212, 1.0, v212
	v_add_f32_e32 v213, 1.0, v213
	v_add_f32_e32 v214, 1.0, v214
	v_add_f32_e32 v215, 1.0, v215
	v_rcp_f32_e32 v212, v212
	v_rcp_f32_e32 v213, v213
	v_rcp_f32_e32 v214, v214
	v_rcp_f32_e32 v215, v215
	s_nop 0
	v_mul_f32_e32 v204, v204, v212
	v_mul_f32_e32 v205, v205, v213
	v_mul_f32_e32 v206, v206, v214
	v_mul_f32_e32 v207, v207, v215
	v_mul_f32_e32 v46, v46, v204
	v_mul_f32_e32 v47, v47, v205
	v_mul_f32_e32 v48, v48, v206
	v_mul_f32_e32 v49, v49, v207
	v_cvt_pk_bf16_f32 v164, v46, v47
	v_cvt_pk_bf16_f32 v165, v48, v49
	global_store_dwordx2 v[152:153], v[164:165], off offset:32
	v_lshlrev_b32_e32 v204, 16, v166
	v_and_b32_e32 v205, 0xffff0000, v166
	v_lshlrev_b32_e32 v206, 16, v167
	v_and_b32_e32 v207, 0xffff0000, v167
	v_mul_f32_e32 v212, 0xbfb8aa3b, v204
	v_mul_f32_e32 v213, 0xbfb8aa3b, v205
	v_mul_f32_e32 v214, 0xbfb8aa3b, v206
	v_mul_f32_e32 v215, 0xbfb8aa3b, v207
	v_exp_f32_e32 v212, v212
	v_exp_f32_e32 v213, v213
	v_exp_f32_e32 v214, v214
	v_exp_f32_e32 v215, v215
	v_mul_f32_e32 v50, v50, v192
	v_mul_f32_e32 v51, v51, v192
	v_mul_f32_e32 v52, v52, v192
	v_mul_f32_e32 v53, v53, v192
	v_add_f32_e32 v212, 1.0, v212
	v_add_f32_e32 v213, 1.0, v213
	v_add_f32_e32 v214, 1.0, v214
	v_add_f32_e32 v215, 1.0, v215
	v_rcp_f32_e32 v212, v212
	v_rcp_f32_e32 v213, v213
	v_rcp_f32_e32 v214, v214
	v_rcp_f32_e32 v215, v215
	s_nop 0
	v_mul_f32_e32 v204, v204, v212
	v_mul_f32_e32 v205, v205, v213
	v_mul_f32_e32 v206, v206, v214
	v_mul_f32_e32 v207, v207, v215
	v_mul_f32_e32 v50, v50, v204
	v_mul_f32_e32 v51, v51, v205
	v_mul_f32_e32 v52, v52, v206
	v_mul_f32_e32 v53, v53, v207
	v_cvt_pk_bf16_f32 v166, v50, v51
	v_cvt_pk_bf16_f32 v167, v52, v53
	global_store_dwordx2 v[152:153], v[166:167], off offset:48
	v_lshlrev_b32_e32 v204, 16, v168
	v_and_b32_e32 v205, 0xffff0000, v168
	v_lshlrev_b32_e32 v206, 16, v169
	v_and_b32_e32 v207, 0xffff0000, v169
	v_mul_f32_e32 v212, 0xbfb8aa3b, v204
	v_mul_f32_e32 v213, 0xbfb8aa3b, v205
	v_mul_f32_e32 v214, 0xbfb8aa3b, v206
	v_mul_f32_e32 v215, 0xbfb8aa3b, v207
	v_exp_f32_e32 v212, v212
	v_exp_f32_e32 v213, v213
	v_exp_f32_e32 v214, v214
	v_exp_f32_e32 v215, v215
	v_mul_f32_e32 v70, v70, v192
	v_mul_f32_e32 v71, v71, v192
	v_mul_f32_e32 v72, v72, v192
	v_mul_f32_e32 v73, v73, v192
	v_add_f32_e32 v212, 1.0, v212
	v_add_f32_e32 v213, 1.0, v213
	v_add_f32_e32 v214, 1.0, v214
	v_add_f32_e32 v215, 1.0, v215
	v_rcp_f32_e32 v212, v212
	v_rcp_f32_e32 v213, v213
	v_rcp_f32_e32 v214, v214
	v_rcp_f32_e32 v215, v215
	s_nop 0
	v_mul_f32_e32 v204, v204, v212
	v_mul_f32_e32 v205, v205, v213
	v_mul_f32_e32 v206, v206, v214
	v_mul_f32_e32 v207, v207, v215
	v_mul_f32_e32 v70, v70, v204
	v_mul_f32_e32 v71, v71, v205
	v_mul_f32_e32 v72, v72, v206
	v_mul_f32_e32 v73, v73, v207
	v_cvt_pk_bf16_f32 v168, v70, v71
	v_cvt_pk_bf16_f32 v169, v72, v73
	global_store_dwordx2 v[152:153], v[168:169], off offset:64
	v_lshlrev_b32_e32 v204, 16, v170
	v_and_b32_e32 v205, 0xffff0000, v170
	v_lshlrev_b32_e32 v206, 16, v171
	v_and_b32_e32 v207, 0xffff0000, v171
	v_mul_f32_e32 v212, 0xbfb8aa3b, v204
	v_mul_f32_e32 v213, 0xbfb8aa3b, v205
	v_mul_f32_e32 v214, 0xbfb8aa3b, v206
	v_mul_f32_e32 v215, 0xbfb8aa3b, v207
	v_exp_f32_e32 v212, v212
	v_exp_f32_e32 v213, v213
	v_exp_f32_e32 v214, v214
	v_exp_f32_e32 v215, v215
	v_mul_f32_e32 v74, v74, v192
	v_mul_f32_e32 v75, v75, v192
	v_mul_f32_e32 v76, v76, v192
	v_mul_f32_e32 v77, v77, v192
	v_add_f32_e32 v212, 1.0, v212
	v_add_f32_e32 v213, 1.0, v213
	v_add_f32_e32 v214, 1.0, v214
	v_add_f32_e32 v215, 1.0, v215
	v_rcp_f32_e32 v212, v212
	v_rcp_f32_e32 v213, v213
	v_rcp_f32_e32 v214, v214
	v_rcp_f32_e32 v215, v215
	s_nop 0
	v_mul_f32_e32 v204, v204, v212
	v_mul_f32_e32 v205, v205, v213
	v_mul_f32_e32 v206, v206, v214
	v_mul_f32_e32 v207, v207, v215
	v_mul_f32_e32 v74, v74, v204
	v_mul_f32_e32 v75, v75, v205
	v_mul_f32_e32 v76, v76, v206
	v_mul_f32_e32 v77, v77, v207
	v_cvt_pk_bf16_f32 v170, v74, v75
	v_cvt_pk_bf16_f32 v171, v76, v77
	global_store_dwordx2 v[152:153], v[170:171], off offset:80
	v_lshlrev_b32_e32 v204, 16, v172
	v_and_b32_e32 v205, 0xffff0000, v172
	v_lshlrev_b32_e32 v206, 16, v173
	v_and_b32_e32 v207, 0xffff0000, v173
	v_mul_f32_e32 v212, 0xbfb8aa3b, v204
	v_mul_f32_e32 v213, 0xbfb8aa3b, v205
	v_mul_f32_e32 v214, 0xbfb8aa3b, v206
	v_mul_f32_e32 v215, 0xbfb8aa3b, v207
	v_exp_f32_e32 v212, v212
	v_exp_f32_e32 v213, v213
	v_exp_f32_e32 v214, v214
	v_exp_f32_e32 v215, v215
	v_mul_f32_e32 v78, v78, v192
	v_mul_f32_e32 v79, v79, v192
	v_mul_f32_e32 v80, v80, v192
	v_mul_f32_e32 v81, v81, v192
	v_add_f32_e32 v212, 1.0, v212
	v_add_f32_e32 v213, 1.0, v213
	v_add_f32_e32 v214, 1.0, v214
	v_add_f32_e32 v215, 1.0, v215
	v_rcp_f32_e32 v212, v212
	v_rcp_f32_e32 v213, v213
	v_rcp_f32_e32 v214, v214
	v_rcp_f32_e32 v215, v215
	s_nop 0
	v_mul_f32_e32 v204, v204, v212
	v_mul_f32_e32 v205, v205, v213
	v_mul_f32_e32 v206, v206, v214
	v_mul_f32_e32 v207, v207, v215
	v_mul_f32_e32 v78, v78, v204
	v_mul_f32_e32 v79, v79, v205
	v_mul_f32_e32 v80, v80, v206
	v_mul_f32_e32 v81, v81, v207
	v_cvt_pk_bf16_f32 v172, v78, v79
	v_cvt_pk_bf16_f32 v173, v80, v81
	global_store_dwordx2 v[152:153], v[172:173], off offset:96
	v_lshlrev_b32_e32 v204, 16, v174
	v_and_b32_e32 v205, 0xffff0000, v174
	v_lshlrev_b32_e32 v206, 16, v175
	v_and_b32_e32 v207, 0xffff0000, v175
	v_mul_f32_e32 v212, 0xbfb8aa3b, v204
	v_mul_f32_e32 v213, 0xbfb8aa3b, v205
	v_mul_f32_e32 v214, 0xbfb8aa3b, v206
	v_mul_f32_e32 v215, 0xbfb8aa3b, v207
	v_exp_f32_e32 v212, v212
	v_exp_f32_e32 v213, v213
	v_exp_f32_e32 v214, v214
	v_exp_f32_e32 v215, v215
	v_mul_f32_e32 v82, v82, v192
	v_mul_f32_e32 v83, v83, v192
	v_mul_f32_e32 v84, v84, v192
	v_mul_f32_e32 v85, v85, v192
	v_add_f32_e32 v212, 1.0, v212
	v_add_f32_e32 v213, 1.0, v213
	v_add_f32_e32 v214, 1.0, v214
	v_add_f32_e32 v215, 1.0, v215
	v_rcp_f32_e32 v212, v212
	v_rcp_f32_e32 v213, v213
	v_rcp_f32_e32 v214, v214
	v_rcp_f32_e32 v215, v215
	s_nop 0
	v_mul_f32_e32 v204, v204, v212
	v_mul_f32_e32 v205, v205, v213
	v_mul_f32_e32 v206, v206, v214
	v_mul_f32_e32 v207, v207, v215
	v_mul_f32_e32 v82, v82, v204
	v_mul_f32_e32 v83, v83, v205
	v_mul_f32_e32 v84, v84, v206
	v_mul_f32_e32 v85, v85, v207
	v_cvt_pk_bf16_f32 v174, v82, v83
	v_cvt_pk_bf16_f32 v175, v84, v85
	global_store_dwordx2 v[152:153], v[174:175], off offset:112
	v_lshlrev_b32_e32 v204, 16, v176
	v_and_b32_e32 v205, 0xffff0000, v176
	v_lshlrev_b32_e32 v206, 16, v177
	v_and_b32_e32 v207, 0xffff0000, v177
	v_mul_f32_e32 v212, 0xbfb8aa3b, v204
	v_mul_f32_e32 v213, 0xbfb8aa3b, v205
	v_mul_f32_e32 v214, 0xbfb8aa3b, v206
	v_mul_f32_e32 v215, 0xbfb8aa3b, v207
	v_exp_f32_e32 v212, v212
	v_exp_f32_e32 v213, v213
	v_exp_f32_e32 v214, v214
	v_exp_f32_e32 v215, v215
	v_mul_f32_e32 v54, v54, v193
	v_mul_f32_e32 v55, v55, v193
	v_mul_f32_e32 v56, v56, v193
	v_mul_f32_e32 v57, v57, v193
	v_add_f32_e32 v212, 1.0, v212
	v_add_f32_e32 v213, 1.0, v213
	v_add_f32_e32 v214, 1.0, v214
	v_add_f32_e32 v215, 1.0, v215
	v_rcp_f32_e32 v212, v212
	v_rcp_f32_e32 v213, v213
	v_rcp_f32_e32 v214, v214
	v_rcp_f32_e32 v215, v215
	s_nop 0
	v_mul_f32_e32 v204, v204, v212
	v_mul_f32_e32 v205, v205, v213
	v_mul_f32_e32 v206, v206, v214
	v_mul_f32_e32 v207, v207, v215
	v_mul_f32_e32 v54, v54, v204
	v_mul_f32_e32 v55, v55, v205
	v_mul_f32_e32 v56, v56, v206
	v_mul_f32_e32 v57, v57, v207
	v_cvt_pk_bf16_f32 v176, v54, v55
	v_cvt_pk_bf16_f32 v177, v56, v57
	global_store_dwordx2 v[154:155], v[176:177], off
	v_lshlrev_b32_e32 v204, 16, v178
	v_and_b32_e32 v205, 0xffff0000, v178
	v_lshlrev_b32_e32 v206, 16, v179
	v_and_b32_e32 v207, 0xffff0000, v179
	v_mul_f32_e32 v212, 0xbfb8aa3b, v204
	v_mul_f32_e32 v213, 0xbfb8aa3b, v205
	v_mul_f32_e32 v214, 0xbfb8aa3b, v206
	v_mul_f32_e32 v215, 0xbfb8aa3b, v207
	v_exp_f32_e32 v212, v212
	v_exp_f32_e32 v213, v213
	v_exp_f32_e32 v214, v214
	v_exp_f32_e32 v215, v215
	v_mul_f32_e32 v58, v58, v193
	v_mul_f32_e32 v59, v59, v193
	v_mul_f32_e32 v60, v60, v193
	v_mul_f32_e32 v61, v61, v193
	v_add_f32_e32 v212, 1.0, v212
	v_add_f32_e32 v213, 1.0, v213
	v_add_f32_e32 v214, 1.0, v214
	v_add_f32_e32 v215, 1.0, v215
	v_rcp_f32_e32 v212, v212
	v_rcp_f32_e32 v213, v213
	v_rcp_f32_e32 v214, v214
	v_rcp_f32_e32 v215, v215
	s_nop 0
	v_mul_f32_e32 v204, v204, v212
	v_mul_f32_e32 v205, v205, v213
	v_mul_f32_e32 v206, v206, v214
	v_mul_f32_e32 v207, v207, v215
	v_mul_f32_e32 v58, v58, v204
	v_mul_f32_e32 v59, v59, v205
	v_mul_f32_e32 v60, v60, v206
	v_mul_f32_e32 v61, v61, v207
	v_cvt_pk_bf16_f32 v178, v58, v59
	v_cvt_pk_bf16_f32 v179, v60, v61
	global_store_dwordx2 v[154:155], v[178:179], off offset:16
	v_lshlrev_b32_e32 v204, 16, v180
	v_and_b32_e32 v205, 0xffff0000, v180
	v_lshlrev_b32_e32 v206, 16, v181
	v_and_b32_e32 v207, 0xffff0000, v181
	v_mul_f32_e32 v212, 0xbfb8aa3b, v204
	v_mul_f32_e32 v213, 0xbfb8aa3b, v205
	v_mul_f32_e32 v214, 0xbfb8aa3b, v206
	v_mul_f32_e32 v215, 0xbfb8aa3b, v207
	v_exp_f32_e32 v212, v212
	v_exp_f32_e32 v213, v213
	v_exp_f32_e32 v214, v214
	v_exp_f32_e32 v215, v215
	v_mul_f32_e32 v62, v62, v193
	v_mul_f32_e32 v63, v63, v193
	v_mul_f32_e32 v64, v64, v193
	v_mul_f32_e32 v65, v65, v193
	v_add_f32_e32 v212, 1.0, v212
	v_add_f32_e32 v213, 1.0, v213
	v_add_f32_e32 v214, 1.0, v214
	v_add_f32_e32 v215, 1.0, v215
	v_rcp_f32_e32 v212, v212
	v_rcp_f32_e32 v213, v213
	v_rcp_f32_e32 v214, v214
	v_rcp_f32_e32 v215, v215
	s_nop 0
	v_mul_f32_e32 v204, v204, v212
	v_mul_f32_e32 v205, v205, v213
	v_mul_f32_e32 v206, v206, v214
	v_mul_f32_e32 v207, v207, v215
	v_mul_f32_e32 v62, v62, v204
	v_mul_f32_e32 v63, v63, v205
	v_mul_f32_e32 v64, v64, v206
	v_mul_f32_e32 v65, v65, v207
	v_cvt_pk_bf16_f32 v180, v62, v63
	v_cvt_pk_bf16_f32 v181, v64, v65
	global_store_dwordx2 v[154:155], v[180:181], off offset:32
	v_lshlrev_b32_e32 v204, 16, v182
	v_and_b32_e32 v205, 0xffff0000, v182
	v_lshlrev_b32_e32 v206, 16, v183
	v_and_b32_e32 v207, 0xffff0000, v183
	v_mul_f32_e32 v212, 0xbfb8aa3b, v204
	v_mul_f32_e32 v213, 0xbfb8aa3b, v205
	v_mul_f32_e32 v214, 0xbfb8aa3b, v206
	v_mul_f32_e32 v215, 0xbfb8aa3b, v207
	v_exp_f32_e32 v212, v212
	v_exp_f32_e32 v213, v213
	v_exp_f32_e32 v214, v214
	v_exp_f32_e32 v215, v215
	v_mul_f32_e32 v66, v66, v193
	v_mul_f32_e32 v67, v67, v193
	v_mul_f32_e32 v68, v68, v193
	v_mul_f32_e32 v69, v69, v193
	v_add_f32_e32 v212, 1.0, v212
	v_add_f32_e32 v213, 1.0, v213
	v_add_f32_e32 v214, 1.0, v214
	v_add_f32_e32 v215, 1.0, v215
	v_rcp_f32_e32 v212, v212
	v_rcp_f32_e32 v213, v213
	v_rcp_f32_e32 v214, v214
	v_rcp_f32_e32 v215, v215
	s_nop 0
	v_mul_f32_e32 v204, v204, v212
	v_mul_f32_e32 v205, v205, v213
	v_mul_f32_e32 v206, v206, v214
	v_mul_f32_e32 v207, v207, v215
	v_mul_f32_e32 v66, v66, v204
	v_mul_f32_e32 v67, v67, v205
	v_mul_f32_e32 v68, v68, v206
	v_mul_f32_e32 v69, v69, v207
	v_cvt_pk_bf16_f32 v182, v66, v67
	v_cvt_pk_bf16_f32 v183, v68, v69
	global_store_dwordx2 v[154:155], v[182:183], off offset:48
	v_lshlrev_b32_e32 v204, 16, v184
	v_and_b32_e32 v205, 0xffff0000, v184
	v_lshlrev_b32_e32 v206, 16, v185
	v_and_b32_e32 v207, 0xffff0000, v185
	v_mul_f32_e32 v212, 0xbfb8aa3b, v204
	v_mul_f32_e32 v213, 0xbfb8aa3b, v205
	v_mul_f32_e32 v214, 0xbfb8aa3b, v206
	v_mul_f32_e32 v215, 0xbfb8aa3b, v207
	v_exp_f32_e32 v212, v212
	v_exp_f32_e32 v213, v213
	v_exp_f32_e32 v214, v214
	v_exp_f32_e32 v215, v215
	v_mul_f32_e32 v86, v86, v193
	v_mul_f32_e32 v87, v87, v193
	v_mul_f32_e32 v88, v88, v193
	v_mul_f32_e32 v89, v89, v193
	v_add_f32_e32 v212, 1.0, v212
	v_add_f32_e32 v213, 1.0, v213
	v_add_f32_e32 v214, 1.0, v214
	v_add_f32_e32 v215, 1.0, v215
	v_rcp_f32_e32 v212, v212
	v_rcp_f32_e32 v213, v213
	v_rcp_f32_e32 v214, v214
	v_rcp_f32_e32 v215, v215
	s_nop 0
	v_mul_f32_e32 v204, v204, v212
	v_mul_f32_e32 v205, v205, v213
	v_mul_f32_e32 v206, v206, v214
	v_mul_f32_e32 v207, v207, v215
	v_mul_f32_e32 v86, v86, v204
	v_mul_f32_e32 v87, v87, v205
	v_mul_f32_e32 v88, v88, v206
	v_mul_f32_e32 v89, v89, v207
	v_cvt_pk_bf16_f32 v184, v86, v87
	v_cvt_pk_bf16_f32 v185, v88, v89
	global_store_dwordx2 v[154:155], v[184:185], off offset:64
	v_lshlrev_b32_e32 v204, 16, v186
	v_and_b32_e32 v205, 0xffff0000, v186
	v_lshlrev_b32_e32 v206, 16, v187
	v_and_b32_e32 v207, 0xffff0000, v187
	v_mul_f32_e32 v212, 0xbfb8aa3b, v204
	v_mul_f32_e32 v213, 0xbfb8aa3b, v205
	v_mul_f32_e32 v214, 0xbfb8aa3b, v206
	v_mul_f32_e32 v215, 0xbfb8aa3b, v207
	v_exp_f32_e32 v212, v212
	v_exp_f32_e32 v213, v213
	v_exp_f32_e32 v214, v214
	v_exp_f32_e32 v215, v215
	v_mul_f32_e32 v90, v90, v193
	v_mul_f32_e32 v91, v91, v193
	v_mul_f32_e32 v92, v92, v193
	v_mul_f32_e32 v93, v93, v193
	v_add_f32_e32 v212, 1.0, v212
	v_add_f32_e32 v213, 1.0, v213
	v_add_f32_e32 v214, 1.0, v214
	v_add_f32_e32 v215, 1.0, v215
	v_rcp_f32_e32 v212, v212
	v_rcp_f32_e32 v213, v213
	v_rcp_f32_e32 v214, v214
	v_rcp_f32_e32 v215, v215
	s_nop 0
	v_mul_f32_e32 v204, v204, v212
	v_mul_f32_e32 v205, v205, v213
	v_mul_f32_e32 v206, v206, v214
	v_mul_f32_e32 v207, v207, v215
	v_mul_f32_e32 v90, v90, v204
	v_mul_f32_e32 v91, v91, v205
	v_mul_f32_e32 v92, v92, v206
	v_mul_f32_e32 v93, v93, v207
	v_cvt_pk_bf16_f32 v186, v90, v91
	v_cvt_pk_bf16_f32 v187, v92, v93
	global_store_dwordx2 v[154:155], v[186:187], off offset:80
	v_lshlrev_b32_e32 v204, 16, v188
	v_and_b32_e32 v205, 0xffff0000, v188
	v_lshlrev_b32_e32 v206, 16, v189
	v_and_b32_e32 v207, 0xffff0000, v189
	v_mul_f32_e32 v212, 0xbfb8aa3b, v204
	v_mul_f32_e32 v213, 0xbfb8aa3b, v205
	v_mul_f32_e32 v214, 0xbfb8aa3b, v206
	v_mul_f32_e32 v215, 0xbfb8aa3b, v207
	v_exp_f32_e32 v212, v212
	v_exp_f32_e32 v213, v213
	v_exp_f32_e32 v214, v214
	v_exp_f32_e32 v215, v215
	v_mul_f32_e32 v94, v94, v193
	v_mul_f32_e32 v95, v95, v193
	v_mul_f32_e32 v96, v96, v193
	v_mul_f32_e32 v97, v97, v193
	v_add_f32_e32 v212, 1.0, v212
	v_add_f32_e32 v213, 1.0, v213
	v_add_f32_e32 v214, 1.0, v214
	v_add_f32_e32 v215, 1.0, v215
	v_rcp_f32_e32 v212, v212
	v_rcp_f32_e32 v213, v213
	v_rcp_f32_e32 v214, v214
	v_rcp_f32_e32 v215, v215
	s_nop 0
	v_mul_f32_e32 v204, v204, v212
	v_mul_f32_e32 v205, v205, v213
	v_mul_f32_e32 v206, v206, v214
	v_mul_f32_e32 v207, v207, v215
	v_mul_f32_e32 v94, v94, v204
	v_mul_f32_e32 v95, v95, v205
	v_mul_f32_e32 v96, v96, v206
	v_mul_f32_e32 v97, v97, v207
	v_cvt_pk_bf16_f32 v188, v94, v95
	v_cvt_pk_bf16_f32 v189, v96, v97
	global_store_dwordx2 v[154:155], v[188:189], off offset:96
	v_lshlrev_b32_e32 v204, 16, v190
	v_and_b32_e32 v205, 0xffff0000, v190
	v_lshlrev_b32_e32 v206, 16, v191
	v_and_b32_e32 v207, 0xffff0000, v191
	v_mul_f32_e32 v212, 0xbfb8aa3b, v204
	v_mul_f32_e32 v213, 0xbfb8aa3b, v205
	v_mul_f32_e32 v214, 0xbfb8aa3b, v206
	v_mul_f32_e32 v215, 0xbfb8aa3b, v207
	v_exp_f32_e32 v212, v212
	v_exp_f32_e32 v213, v213
	v_exp_f32_e32 v214, v214
	v_exp_f32_e32 v215, v215
	v_mul_f32_e32 v98, v98, v193
	v_mul_f32_e32 v99, v99, v193
	v_mul_f32_e32 v100, v100, v193
	v_mul_f32_e32 v101, v101, v193
	v_add_f32_e32 v212, 1.0, v212
	v_add_f32_e32 v213, 1.0, v213
	v_add_f32_e32 v214, 1.0, v214
	v_add_f32_e32 v215, 1.0, v215
	v_rcp_f32_e32 v212, v212
	v_rcp_f32_e32 v213, v213
	v_rcp_f32_e32 v214, v214
	v_rcp_f32_e32 v215, v215
	s_nop 0
	v_mul_f32_e32 v204, v204, v212
	v_mul_f32_e32 v205, v205, v213
	v_mul_f32_e32 v206, v206, v214
	v_mul_f32_e32 v207, v207, v215
	v_mul_f32_e32 v98, v98, v204
	v_mul_f32_e32 v99, v99, v205
	v_mul_f32_e32 v100, v100, v206
	v_mul_f32_e32 v101, v101, v207
	v_cvt_pk_bf16_f32 v190, v98, v99
	v_cvt_pk_bf16_f32 v191, v100, v101
	global_store_dwordx2 v[154:155], v[190:191], off offset:112
	s_cmpk_gt_i32 s6, 0x40f
	s_cbranch_scc0 .LBB0_937
